# prologue x-row loop: prefetch next row (test)
# speedup vs baseline: 1.0101x; 1.0039x over previous
.LBB0_269:
	v_readlane_b32 s1, v253, 63
	s_lshl_b32 s0, s66, 7
	s_and_b32 s1, s1, 0xf8
	s_and_b32 s0, s0, 0xfffff000
	s_add_i32 s1, s1, s96
	s_add_i32 s5, s0, 0x1000
	s_add_i32 s6, s1, s0
	s_cmpk_eq_i32 s68, 0x100
	s_cselect_b64 s[2:3], -1, 0
	s_and_b64 s[0:1], s[2:3], exec
	s_cselect_b32 s7, s5, 0x8000
	s_cselect_b32 s12, s6, s10
	s_cmp_ge_i32 s12, s7
	s_mov_b32 s6, 0x8000
	s_cbranch_scc1 .LBB0_274
	v_mbcnt_lo_u32_b32 v2, -1, 0
	v_mbcnt_hi_u32_b32 v2, -1, v2
	v_and_b32_e32 v3, 64, v2
	v_add_u32_e32 v3, 64, v3
	v_xor_b32_e32 v4, 1, v2
	v_cmp_lt_i32_e32 vcc, v4, v3
	s_and_b64 s[0:1], s[2:3], exec
	s_cselect_b32 s13, 0x100, s4
	v_cndmask_b32_e32 v4, v2, v4, vcc
	v_lshlrev_b32_e32 v24, 2, v4
	v_xor_b32_e32 v4, 2, v2
	v_cmp_lt_i32_e32 vcc, v4, v3
	s_lshl_b32 s0, s66, 8
	s_and_b32 s5, s66, 31
	v_cndmask_b32_e32 v4, v2, v4, vcc
	v_lshlrev_b32_e32 v25, 2, v4
	v_xor_b32_e32 v4, 4, v2
	v_cmp_lt_i32_e32 vcc, v4, v3
	s_and_b32 s4, s0, 0xffffe000
	s_lshl_b32 s5, s5, 4
	v_cndmask_b32_e32 v4, v2, v4, vcc
	v_lshlrev_b32_e32 v26, 2, v4
	v_xor_b32_e32 v4, 8, v2
	v_cmp_lt_i32_e32 vcc, v4, v3
	s_or_b32 s4, s4, s5
	s_lshl_b32 s5, s96, 1
	v_cndmask_b32_e32 v4, v2, v4, vcc
	v_lshlrev_b32_e32 v27, 2, v4
	v_xor_b32_e32 v4, 16, v2
	v_cmp_lt_i32_e32 vcc, v4, v3
	v_lshlrev_b32_e32 v18, 4, v177
	v_mov_b32_e32 v19, 0
	v_cndmask_b32_e32 v4, v2, v4, vcc
	v_lshlrev_b32_e32 v28, 2, v4
	v_xor_b32_e32 v4, 32, v2
	v_cmp_lt_i32_e32 vcc, v4, v3
	v_readlane_b32 s8, v253, 52
	s_add_i32 s4, s4, s5
	v_cndmask_b32_e32 v2, v2, v4, vcc
	v_lshl_add_u64 v[20:21], s[48:49], 0, v[18:19]
	v_lshlrev_b32_e32 v18, 3, v177
	v_readlane_b32 s9, v253, 53
	s_sub_i32 s4, s4, s12
	v_lshlrev_b32_e32 v29, 2, v2
	v_cmp_eq_u32_e64 s[0:1], 0, v177
	v_lshl_add_u64 v[22:23], s[8:9], 0, v[18:19]
	s_add_i32 s14, s4, 0xf00
	v_mov_b32_e32 v18, 0x358637bd
	s_mov_b32 s15, 0xf800000
	v_mov_b32_e32 v30, 0x260
	s_movk_i32 s16, 0x7fff
	s_mov_b32 s17, 0xffff0000
	s_and_b64 s[4:5], s[2:3], exec
	s_cselect_b32 s18, s14, s12
	s_ashr_i32 s19, s18, 31
	s_lshl_b64 s[4:5], s[18:19], 12
	v_lshl_add_u64 v[116:117], v[20:21], 0, s[4:5]
	global_load_dwordx4 v[100:103], v[116:117], off nt
	global_load_dwordx4 v[104:107], v[116:117], off offset:1024 nt
	global_load_dwordx4 v[108:111], v[116:117], off offset:2048 nt
	global_load_dwordx4 v[112:115], v[116:117], off offset:3072 nt
	s_waitcnt vmcnt(0)
	s_branch .Lxr_body
.LBB0_271:
	s_or_b64 exec, exec, s[4:5]
	v_div_scale_f32 v32, s[4:5], v31, v31, 1.0
	v_rcp_f32_e32 v33, v32
	s_lshl_b64 s[4:5], s[10:11], 10
	s_add_i32 s12, s12, s13
	s_sub_i32 s14, s14, s13
	v_fma_f32 v34, -v32, v33, 1.0
	v_fmac_f32_e32 v33, v34, v33
	v_div_scale_f32 v34, vcc, 1.0, v31, 1.0
	v_mul_f32_e32 v35, v34, v33
	v_fma_f32 v36, -v32, v35, v34
	v_fmac_f32_e32 v35, v36, v33
	v_fma_f32 v32, -v32, v35, v34
	v_div_fmas_f32 v32, v32, v33, v35
	v_div_fixup_f32 v31, v32, v31, 1.0
	v_mul_f32_e32 v14, v14, v31
	v_mul_f32_e32 v15, v15, v31
	v_bfe_u32 v34, v14, 16, 1
	v_add3_u32 v14, v14, v34, s16
	v_bfe_u32 v34, v15, 16, 1
	v_lshrrev_b32_e32 v14, 16, v14
	v_add3_u32 v15, v15, v34, s16
	v_and_or_b32 v14, v15, s17, v14
	v_mul_f32_e32 v15, v16, v31
	v_mul_f32_e32 v16, v17, v31
	v_bfe_u32 v17, v15, 16, 1
	v_add3_u32 v15, v15, v17, s16
	v_bfe_u32 v17, v16, 16, 1
	v_lshrrev_b32_e32 v15, 16, v15
	v_add3_u32 v16, v16, v17, s16
	v_lshl_add_u64 v[32:33], s[4:5], 1, v[22:23]
	v_and_or_b32 v15, v16, s17, v15
	v_mul_f32_e32 v10, v10, v31
	global_store_dwordx2 v[32:33], v[14:15], off
	v_mul_f32_e32 v11, v11, v31
	v_bfe_u32 v14, v10, 16, 1
	v_add3_u32 v10, v10, v14, s16
	v_bfe_u32 v14, v11, 16, 1
	v_lshrrev_b32_e32 v10, 16, v10
	v_add3_u32 v11, v11, v14, s16
	v_and_or_b32 v10, v11, s17, v10
	v_mul_f32_e32 v11, v12, v31
	v_mul_f32_e32 v12, v13, v31
	v_bfe_u32 v13, v11, 16, 1
	v_add3_u32 v11, v11, v13, s16
	v_bfe_u32 v13, v12, 16, 1
	v_lshrrev_b32_e32 v11, 16, v11
	v_add3_u32 v12, v12, v13, s16
	v_and_or_b32 v11, v12, s17, v11
	v_mul_f32_e32 v6, v6, v31
	global_store_dwordx2 v[32:33], v[10:11], off offset:512
	v_mul_f32_e32 v7, v7, v31
	v_bfe_u32 v10, v6, 16, 1
	v_add3_u32 v6, v6, v10, s16
	v_bfe_u32 v10, v7, 16, 1
	v_lshrrev_b32_e32 v6, 16, v6
	v_add3_u32 v7, v7, v10, s16
	v_and_or_b32 v6, v7, s17, v6
	v_mul_f32_e32 v7, v8, v31
	v_mul_f32_e32 v8, v9, v31
	v_bfe_u32 v9, v7, 16, 1
	v_add3_u32 v7, v7, v9, s16
	v_bfe_u32 v9, v8, 16, 1
	v_lshrrev_b32_e32 v7, 16, v7
	v_add3_u32 v8, v8, v9, s16
	v_and_or_b32 v7, v8, s17, v7
	v_mul_f32_e32 v2, v2, v31
	global_store_dwordx2 v[32:33], v[6:7], off offset:1024
	v_mul_f32_e32 v3, v3, v31
	v_bfe_u32 v6, v2, 16, 1
	v_add3_u32 v2, v2, v6, s16
	v_bfe_u32 v6, v3, 16, 1
	v_lshrrev_b32_e32 v2, 16, v2
	v_add3_u32 v3, v3, v6, s16
	v_and_or_b32 v2, v3, s17, v2
	v_mul_f32_e32 v3, v4, v31
	v_mul_f32_e32 v4, v5, v31
	v_bfe_u32 v5, v3, 16, 1
	v_add3_u32 v3, v3, v5, s16
	v_bfe_u32 v5, v4, 16, 1
	v_lshrrev_b32_e32 v3, 16, v3
	v_add3_u32 v4, v4, v5, s16
	v_and_or_b32 v3, v4, s17, v3
	s_cmp_lt_i32 s12, s7
	global_store_dwordx2 v[32:33], v[2:3], off offset:1536
	s_cbranch_scc0 .LBB0_274
.LBB0_272:
	s_waitcnt vmcnt(5)
.Lxr_body:
	v_mov_b32_e32 v14, v100
	v_mov_b32_e32 v15, v101
	v_mov_b32_e32 v16, v102
	v_mov_b32_e32 v17, v103
	v_mov_b32_e32 v10, v104
	v_mov_b32_e32 v11, v105
	v_mov_b32_e32 v12, v106
	v_mov_b32_e32 v13, v107
	v_mov_b32_e32 v6, v108
	v_mov_b32_e32 v7, v109
	v_mov_b32_e32 v8, v110
	v_mov_b32_e32 v9, v111
	v_mov_b32_e32 v2, v112
	v_mov_b32_e32 v3, v113
	v_mov_b32_e32 v4, v114
	v_mov_b32_e32 v5, v115
	s_and_b64 s[4:5], s[2:3], exec
	s_cselect_b32 s10, s14, s12
	s_ashr_i32 s11, s10, 31
	s_add_i32 s18, s12, s13
	s_cmp_lt_i32 s18, s7
	s_cbranch_scc0 .Lxr_skip
	s_sub_i32 s19, s14, s13
	s_and_b64 s[4:5], s[2:3], exec
	s_cselect_b32 s18, s19, s18
	s_ashr_i32 s19, s18, 31
	s_lshl_b64 s[4:5], s[18:19], 12
	v_lshl_add_u64 v[116:117], v[20:21], 0, s[4:5]
	global_load_dwordx4 v[100:103], v[116:117], off nt
	global_load_dwordx4 v[104:107], v[116:117], off offset:1024 nt
	global_load_dwordx4 v[108:111], v[116:117], off offset:2048 nt
	global_load_dwordx4 v[112:115], v[116:117], off offset:3072 nt
.Lxr_skip:
	v_mul_f32_e32 v31, v15, v15
	v_mul_f32_e32 v32, v17, v17
	v_mul_f32_e32 v33, v11, v11
	v_mul_f32_e32 v34, v13, v13
	v_mul_f32_e32 v35, v7, v7
	v_mul_f32_e32 v36, v9, v9
	v_fmac_f32_e32 v31, v14, v14
	v_fmac_f32_e32 v32, v16, v16
	v_fmac_f32_e32 v33, v10, v10
	v_fmac_f32_e32 v34, v12, v12
	v_mul_f32_e32 v37, v3, v3
	v_mul_f32_e32 v38, v5, v5
	v_fmac_f32_e32 v35, v6, v6
	v_fmac_f32_e32 v36, v8, v8
	v_add_f32_e32 v31, v31, v32
	v_add_f32_e32 v32, v33, v34
	v_fmac_f32_e32 v37, v2, v2
	v_fmac_f32_e32 v38, v4, v4
	v_add_f32_e32 v33, v35, v36
	v_add_f32_e32 v31, v31, v32
	v_add_f32_e32 v34, v37, v38
	v_add_f32_e32 v31, v31, v33
	v_add_f32_e32 v31, v31, v34
	ds_bpermute_b32 v32, v24, v31
	s_waitcnt lgkmcnt(0)
	v_add_f32_e32 v31, v31, v32
	ds_bpermute_b32 v32, v25, v31
	s_waitcnt lgkmcnt(0)
	v_add_f32_e32 v31, v31, v32
	ds_bpermute_b32 v32, v26, v31
	s_waitcnt lgkmcnt(0)
	v_add_f32_e32 v31, v31, v32
	ds_bpermute_b32 v32, v27, v31
	s_waitcnt lgkmcnt(0)
	v_add_f32_e32 v31, v31, v32
	ds_bpermute_b32 v32, v28, v31
	s_waitcnt lgkmcnt(0)
	v_add_f32_e32 v31, v31, v32
	ds_bpermute_b32 v32, v29, v31
	s_waitcnt lgkmcnt(0)
	v_add_f32_e32 v31, v31, v32
	v_fmamk_f32 v31, v31, 0x3a800000, v18
	v_mul_f32_e32 v32, 0x4f800000, v31
	v_cmp_gt_f32_e32 vcc, s15, v31
	s_nop 1
	v_cndmask_b32_e32 v31, v31, v32, vcc
	v_sqrt_f32_e32 v32, v31
	s_nop 0
	v_add_u32_e32 v33, -1, v32
	v_add_u32_e32 v34, 1, v32
	v_fma_f32 v35, -v33, v32, v31
	v_fma_f32 v36, -v34, v32, v31
	v_cmp_ge_f32_e64 s[4:5], 0, v35
	s_nop 1
	v_cndmask_b32_e64 v32, v32, v33, s[4:5]
	v_cmp_lt_f32_e64 s[4:5], 0, v36
	s_nop 1
	v_cndmask_b32_e64 v32, v32, v34, s[4:5]
	v_mul_f32_e32 v33, 0x37800000, v32
	v_cndmask_b32_e32 v32, v32, v33, vcc
	v_cmp_class_f32_e32 vcc, v31, v30
	s_nop 1
	v_cndmask_b32_e32 v31, v32, v31, vcc
	s_and_saveexec_b64 s[4:5], s[0:1]
	s_cbranch_execz .LBB0_271
	s_lshl_b64 s[18:19], s[10:11], 2
	s_add_u32 s18, s75, s18
	s_addc_u32 s19, s69, s19
	global_store_dword v19, v31, s[18:19]
	s_branch .LBB0_271
